# restored the 1-wait-state pad between an m0 write and its LDS-DMA at one site of the attention c=1 loop (hazard fix, no functional change)
# speedup vs baseline: 1.0062x; 1.0025x over previous
.LBB0_916:
	s_cmp_lt_u32 s47, 62
	s_cselect_b32 s44, s40, s21
	s_add_i32 s44, s44, s41
	s_addk_i32 s44, 0xff80
	s_ashr_i32 s45, s44, 31
	s_lshl_b64 s[44:45], s[44:45], 1
	s_add_u32 s44, s39, s44
	s_addc_u32 s45, s67, s45
	s_add_i32 s49, s46, 0xffffc000
	s_and_b32 s49, s49, 0xc000
	s_add_i32 s49, s58, s49
	s_add_i32 m0, s49, 0xc000
	s_nop 0
	global_load_lds_dwordx4 v196, s[44:45]
	v_lshl_add_u64 v[140:141], s[44:45], 0, v[192:193]
	s_add_i32 m0, s49, 0xc400
	s_add_i32 s44, s48, 1
	global_load_lds_dwordx4 v[140:141], off
	s_cmp_lg_u32 s48, 2
	s_cselect_b32 s48, s44, 0
	s_lshl_b32 s44, s48, 14
	s_and_b32 s49, s46, 0xc000
	s_add_i32 s68, s44, 0
	s_add_i32 s44, s49, 0
	v_add_u32_e32 v156, s44, v206
	ds_read_b128 v[140:143], v156 offset:49152
	ds_read_b128 v[148:151], v156 offset:53248
	ds_read_b128 v[152:155], v156 offset:57344
	ds_read_b128 v[156:159], v156 offset:61440
	s_waitcnt lgkmcnt(0)
	v_mfma_f32_32x32x16_bf16 v[80:95], v[140:143], v[144:147], v[80:95]
	v_xad_u32 v177, v206, 32, s44
	ds_read_b128 v[140:143], v177 offset:49152
	v_mfma_f32_32x32x16_bf16 v[64:79], v[148:151], v[144:147], v[64:79]
	ds_read_b128 v[148:151], v177 offset:53248
	v_mfma_f32_32x32x16_bf16 v[16:31], v[152:155], v[144:147], v[16:31]
	ds_read_b128 v[152:155], v177 offset:57344
	v_mfma_f32_32x32x16_bf16 v[0:15], v[156:159], v[144:147], v[0:15]
	ds_read_b128 v[144:147], v177 offset:61440
	s_waitcnt lgkmcnt(0)
	v_mfma_f32_32x32x16_bf16 v[80:95], v[140:143], v[128:131], v[80:95]
	v_xad_u32 v156, v206, 64, s44
	ds_read_b128 v[140:143], v156 offset:49152
	v_mfma_f32_32x32x16_bf16 v[64:79], v[148:151], v[128:131], v[64:79]
	ds_read_b128 v[148:151], v156 offset:53248
	v_mfma_f32_32x32x16_bf16 v[16:31], v[152:155], v[128:131], v[16:31]
	ds_read_b128 v[152:155], v156 offset:57344
	v_mfma_f32_32x32x16_bf16 v[0:15], v[144:147], v[128:131], v[0:15]
	ds_read_b128 v[128:131], v156 offset:61440
	s_waitcnt lgkmcnt(0)
	v_mfma_f32_32x32x16_bf16 v[80:95], v[140:143], v[132:135], v[80:95]
	v_add_u32_e32 v156, s44, v209
	ds_read_b128 v[140:143], v156 offset:49152
	v_mfma_f32_32x32x16_bf16 v[64:79], v[148:151], v[132:135], v[64:79]
	ds_read_b128 v[144:147], v156 offset:53248
	v_mfma_f32_32x32x16_bf16 v[16:31], v[152:155], v[132:135], v[16:31]
	ds_read_b128 v[148:151], v156 offset:57344
	v_mfma_f32_32x32x16_bf16 v[0:15], v[128:131], v[132:135], v[0:15]
	ds_read_b128 v[128:131], v156 offset:61440
	s_waitcnt lgkmcnt(0)
	v_mfma_f32_32x32x16_bf16 v[80:95], v[140:143], v[136:139], v[80:95]
	v_add_u32_e32 v140, s68, v205
	ds_read_b128 v[132:135], v140
	v_mfma_f32_32x32x16_bf16 v[64:79], v[144:147], v[136:139], v[64:79]
	ds_read_b128 v[140:143], v140 offset:8192
	v_mfma_f32_32x32x16_bf16 v[16:31], v[148:151], v[136:139], v[16:31]
	v_xad_u32 v144, v205, 32, s68
	ds_read_b128 v[176:179], v144
	v_mfma_f32_32x32x16_bf16 v[0:15], v[128:131], v[136:139], v[0:15]
	ds_read_b128 v[182:185], v144 offset:8192
	s_waitcnt lgkmcnt(0)
	v_mfma_f32_32x32x16_bf16 v[144:159], v[132:135], v[160:163], 0
	v_xad_u32 v216, v205, 64, s68
	ds_read_b128 v[186:189], v216
	v_exp_f32_e32 v220, v112
	v_exp_f32_e32 v221, v113
	v_exp_f32_e32 v222, v114
	v_exp_f32_e32 v223, v115
	v_mfma_f32_32x32x16_bf16 v[128:143], v[140:143], v[160:163], 0
	ds_read_b128 v[216:219], v216 offset:8192
	v_exp_f32_e32 v224, v116
	v_exp_f32_e32 v225, v117
	v_exp_f32_e32 v226, v118
	v_exp_f32_e32 v227, v119
	v_mfma_f32_32x32x16_bf16 v[144:159], v[176:179], v[164:167], v[144:159]
	v_add_u32_e32 v181, s68, v213
	ds_read_b128 v[116:119], v181
	v_exp_f32_e32 v228, v120
	v_exp_f32_e32 v229, v121
	v_exp_f32_e32 v230, v122
	v_exp_f32_e32 v231, v123
	v_cvt_pk_bf16_f32 v112, v220, v221
	v_cvt_pk_bf16_f32 v113, v222, v223
	v_cvt_pk_bf16_f32 v114, v224, v225
	v_cvt_pk_bf16_f32 v115, v226, v227
	v_pk_add_f32 v[122:123], v[226:227], v[222:223]
	v_pk_add_f32 v[120:121], v[224:225], v[220:221]
	v_mfma_f32_32x32x16_bf16 v[128:143], v[182:185], v[164:167], v[128:143]
	ds_read_b128 v[176:179], v181 offset:8192
	v_exp_f32_e32 v124, v124
	v_exp_f32_e32 v125, v125
	v_exp_f32_e32 v126, v126
	v_exp_f32_e32 v127, v127
	s_waitcnt lgkmcnt(0)
	v_mfma_f32_32x32x16_bf16 v[144:159], v[186:189], v[168:171], v[144:159]
	v_add_f32_e64 v122, v230, v122
	v_add_f32_e64 v123, v231, v123
	v_add_f32_e64 v120, v228, v120
	v_add_f32_e64 v121, v229, v121
	v_exp_f32_e32 v182, v96
	v_exp_f32_e32 v183, v97
	v_exp_f32_e32 v184, v98
	v_exp_f32_e32 v185, v99
	v_cvt_pk_bf16_f32 v96, v228, v229
	v_cvt_pk_bf16_f32 v97, v230, v231
	v_cvt_pk_bf16_f32 v98, v124, v125
	v_cvt_pk_bf16_f32 v99, v126, v127
	v_pk_add_f32 v[122:123], v[126:127], v[122:123]
	v_pk_add_f32 v[120:121], v[124:125], v[120:121]
	v_mfma_f32_32x32x16_bf16 v[128:143], v[216:219], v[168:171], v[128:143]
	v_exp_f32_e32 v124, v100
	v_exp_f32_e32 v125, v101
	v_exp_f32_e32 v126, v102
	v_exp_f32_e32 v127, v103
	v_mfma_f32_32x32x16_bf16 v[144:159], v[116:119], v[172:175], v[144:159]
	v_exp_f32_e32 v186, v104
	v_exp_f32_e32 v187, v105
	v_exp_f32_e32 v188, v106
	v_exp_f32_e32 v189, v107
	v_pk_add_f32 v[106:107], v[184:185], v[122:123]
	v_pk_add_f32 v[104:105], v[182:183], v[120:121]
	v_cvt_pk_bf16_f32 v100, v182, v183
	v_cvt_pk_bf16_f32 v101, v184, v185
	v_cvt_pk_bf16_f32 v102, v124, v125
	v_cvt_pk_bf16_f32 v103, v126, v127
	v_pk_add_f32 v[118:119], v[126:127], v[106:107]
	v_pk_add_f32 v[116:117], v[124:125], v[104:105]
	v_mfma_f32_32x32x16_bf16 v[128:143], v[176:179], v[172:175], v[128:143]
	v_exp_f32_e32 v120, v108
	v_exp_f32_e32 v121, v109
	v_exp_f32_e32 v122, v110
	v_exp_f32_e32 v123, v111
	v_pk_add_f32 v[110:111], v[188:189], v[118:119]
	v_pk_add_f32 v[108:109], v[186:187], v[116:117]
	v_cvt_pk_bf16_f32 v104, v186, v187
	v_cvt_pk_bf16_f32 v105, v188, v189
	v_cvt_pk_bf16_f32 v106, v120, v121
	v_cvt_pk_bf16_f32 v107, v122, v123
	s_mov_b64 s[44:45], -1
	s_and_b64 vcc, exec, s[42:43]
	v_pk_add_f32 v[178:179], v[122:123], v[110:111]
	v_pk_add_f32 v[176:177], v[120:121], v[108:109]
	s_cbranch_vccz .LBB0_918
	s_waitcnt vmcnt(2) lgkmcnt(0)
	s_mov_b64 s[44:45], 0
